# retention sample tile loop: PV section with grouped double-buffered V-fragment LDS reads (was read-wait-mfma per fragment); hyena e-loop pipelined
# speedup vs baseline: 1.0041x; 1.0024x over previous
.LBB0_722:
	v_mov_b32_e32 v161, v78
	v_add_u32_e32 v126, 0x3f80, v77
	v_cmp_gt_u32_e32 vcc, 64, v161
	v_mad_u32_u24 v162, v161, s83, v65
	s_nop 0
	v_cndmask_b32_e32 v127, v214, v162, vcc
	ds_read_b128 v[142:145], v126
	ds_read_b128 v[170:173], v127
	ds_read_b128 v[146:149], v126 offset:32
	ds_read_b128 v[174:177], v127 offset:32
	ds_read_b128 v[150:153], v126 offset:64
	ds_read_b128 v[178:181], v127 offset:64
	ds_read_b128 v[154:157], v126 offset:96
	ds_read_b128 v[182:185], v127 offset:96
	s_movk_i32 s0, 47
.Lhy_s_loop:
	v_add_u32_e32 v161, -1, v161
	v_add_u32_e32 v126, 0xffffff80, v126
	v_cmp_gt_u32_e32 vcc, 64, v161
	v_mad_u32_u24 v162, v161, s83, v65
	s_nop 0
	v_cndmask_b32_e32 v160, v214, v162, vcc
	ds_read_b128 v[216:219], v126
	ds_read_b128 v[232:235], v160
	ds_read_b128 v[220:223], v126 offset:32
	ds_read_b128 v[236:239], v160 offset:32
	ds_read_b128 v[224:227], v126 offset:64
	ds_read_b128 v[240:243], v160 offset:64
	ds_read_b128 v[228:231], v126 offset:96
	ds_read_b128 v[244:247], v160 offset:96
	s_waitcnt lgkmcnt(8)
	v_mfma_f32_32x32x16_bf16 v[0:15], v[142:145], v[170:173], v[0:15]
	v_mfma_f32_32x32x16_bf16 v[0:15], v[146:149], v[174:177], v[0:15]
	v_mfma_f32_32x32x16_bf16 v[0:15], v[150:153], v[178:181], v[0:15]
	v_mfma_f32_32x32x16_bf16 v[0:15], v[154:157], v[182:185], v[0:15]
	v_add_u32_e32 v161, -1, v161
	v_add_u32_e32 v126, 0xffffff80, v126
	v_cmp_gt_u32_e32 vcc, 64, v161
	v_mad_u32_u24 v162, v161, s83, v65
	s_nop 0
	v_cndmask_b32_e32 v127, v214, v162, vcc
	ds_read_b128 v[142:145], v126
	ds_read_b128 v[170:173], v127
	ds_read_b128 v[146:149], v126 offset:32
	ds_read_b128 v[174:177], v127 offset:32
	ds_read_b128 v[150:153], v126 offset:64
	ds_read_b128 v[178:181], v127 offset:64
	ds_read_b128 v[154:157], v126 offset:96
	ds_read_b128 v[182:185], v127 offset:96
	s_waitcnt lgkmcnt(8)
	v_mfma_f32_32x32x16_bf16 v[0:15], v[216:219], v[232:235], v[0:15]
	v_mfma_f32_32x32x16_bf16 v[0:15], v[220:223], v[236:239], v[0:15]
	v_mfma_f32_32x32x16_bf16 v[0:15], v[224:227], v[240:243], v[0:15]
	v_mfma_f32_32x32x16_bf16 v[0:15], v[228:231], v[244:247], v[0:15]
	s_add_i32 s0, s0, -1
	s_cmp_lg_u32 s0, 0
	s_cbranch_scc1 .Lhy_s_loop
	s_waitcnt lgkmcnt(0)
	v_mfma_f32_32x32x16_bf16 v[0:15], v[142:145], v[170:173], v[0:15]
	v_mfma_f32_32x32x16_bf16 v[0:15], v[146:149], v[174:177], v[0:15]
	v_mfma_f32_32x32x16_bf16 v[0:15], v[150:153], v[178:181], v[0:15]
	v_mfma_f32_32x32x16_bf16 v[0:15], v[154:157], v[182:185], v[0:15]
	s_and_b64 s[0:1], s[88:89], exec
	s_cselect_b32 s0, s90, s82
	s_lshl_b32 s0, s0, 1
	s_add_u32 s0, s48, s0
	s_addc_u32 s1, s49, 0
	v_lshl_add_u64 v[96:97], v[22:23], 1, s[0:1]
	v_mov_b32_e32 v61, v112
	v_lshl_add_u64 v[96:97], v[96:97], 0, v[60:61]
	v_mov_b32_e32 v63, v112
	v_lshl_add_u64 v[96:97], v[96:97], 0, v[62:63]
	s_mov_b64 s[0:1], 0x4000
	v_lshl_add_u64 v[98:99], v[96:97], 0, s[0:1]
	s_movk_i32 s0, 0x4000
	v_add_co_u32_e32 v96, vcc, s0, v96
	s_nop 1
	v_addc_co_u32_e32 v97, vcc, 0, v97, vcc
	s_barrier
	global_load_dwordx2 v[96:97], v[96:97], off
	s_movk_i32 s0, 0x400
	s_mov_b64 s[88:89], 0
	s_and_b64 vcc, exec, s[12:13]
	s_waitcnt vmcnt(0)
	v_lshlrev_b32_e32 v100, 16, v96
	v_and_b32_e32 v101, 0xffff0000, v96
	v_lshlrev_b32_e32 v96, 16, v97
	v_and_b32_e32 v97, 0xffff0000, v97
	v_pk_mul_f32 v[0:1], v[0:1], v[100:101]
	v_pk_mul_f32 v[2:3], v[2:3], v[96:97]
	v_cvt_pk_bf16_f32 v0, v0, v1
	v_cvt_pk_bf16_f32 v1, v2, v3
	global_load_dwordx2 v[2:3], v[98:99], off offset:16
	s_waitcnt vmcnt(0)
	v_lshlrev_b32_e32 v96, 16, v2
	v_and_b32_e32 v97, 0xffff0000, v2
	v_pk_mul_f32 v[4:5], v[4:5], v[96:97]
	s_nop 0
	v_cvt_pk_bf16_f32 v2, v4, v5
	v_lshlrev_b32_e32 v4, 16, v3
	v_and_b32_e32 v5, 0xffff0000, v3
	v_pk_mul_f32 v[4:5], v[6:7], v[4:5]
	s_nop 0
	v_cvt_pk_bf16_f32 v3, v4, v5
	ds_write2_b64 v76, v[0:1], v[2:3] offset1:2
	global_load_dwordx2 v[0:1], v[98:99], off offset:32
	s_waitcnt vmcnt(0)
	v_lshlrev_b32_e32 v2, 16, v0
	v_and_b32_e32 v3, 0xffff0000, v0
	v_pk_mul_f32 v[2:3], v[8:9], v[2:3]
	s_nop 0
	v_cvt_pk_bf16_f32 v0, v2, v3
	v_lshlrev_b32_e32 v2, 16, v1
	v_and_b32_e32 v3, 0xffff0000, v1
	v_pk_mul_f32 v[2:3], v[10:11], v[2:3]
	s_nop 0
	v_cvt_pk_bf16_f32 v1, v2, v3
	global_load_dwordx2 v[2:3], v[98:99], off offset:48
	s_waitcnt vmcnt(0)
	v_lshlrev_b32_e32 v4, 16, v2
	v_and_b32_e32 v5, 0xffff0000, v2
	v_pk_mul_f32 v[4:5], v[12:13], v[4:5]
	s_nop 0
	v_cvt_pk_bf16_f32 v2, v4, v5
	v_lshlrev_b32_e32 v4, 16, v3
	v_and_b32_e32 v5, 0xffff0000, v3
	v_pk_mul_f32 v[4:5], v[14:15], v[4:5]
	s_nop 0
	v_cvt_pk_bf16_f32 v3, v4, v5
	ds_write2_b64 v76, v[0:1], v[2:3] offset0:4 offset1:6
	s_waitcnt lgkmcnt(0)
	s_barrier
	s_cbranch_vccz .LBB0_565
	s_lshl_b32 s0, s90, 1
	v_readlane_b32 s2, v254, 39
	v_readlane_b32 s3, v254, 40
	s_add_u32 s0, s2, s0
	s_addc_u32 s1, s3, 0
	v_lshlrev_b32_e32 v0, 1, v16
	v_mov_b32_e32 v1, v112
	v_lshl_add_u64 v[0:1], s[0:1], 0, v[0:1]
	s_mov_b64 s[0:1], 0x4000
	v_lshl_add_u64 v[4:5], v[0:1], 0, s[0:1]
	v_add_u32_e32 v0, v17, v67
	ds_read_b128 v[0:3], v0
	v_lshl_add_u64 v[6:7], v[50:51], 1, v[4:5]
	s_mov_b32 s96, 0
	s_movk_i32 s71, 0x90
	v_lshl_add_u64 v[4:5], v[42:43], 1, v[4:5]
	s_waitcnt lgkmcnt(0)
	global_store_dwordx4 v[6:7], v[0:3], off
	v_readlane_b32 s88, v255, 25
	s_movk_i32 s97, 0x5eed
	v_add_u32_e32 v0, v17, v66
	ds_read_b128 v[0:3], v0
	v_readlane_b32 s38, v253, 1
	s_movk_i32 s74, 0x2400
	s_movk_i32 s64, 0x1fff
	v_readlane_b32 s89, v255, 26
	s_waitcnt lgkmcnt(0)
	global_store_dwordx4 v[4:5], v[0:3], off
	s_barrier
	v_readlane_b32 s39, v253, 2
	s_branch .LBB0_466

.LBB0_803:
	s_nop 6
	v_mul_f32_e32 v71, v79, v188
	v_cvt_pk_bf16_f32 v64, v174, v175
	v_cvt_pk_bf16_f32 v65, v176, v177
	v_cvt_pk_bf16_f32 v66, v178, v179
	v_cvt_pk_bf16_f32 v67, v180, v181
	v_add_u32_e32 v175, s37, v217
	v_cvt_pk_bf16_f32 v68, v182, v183
	v_cvt_pk_bf16_f32 v69, v184, v185
	v_cvt_pk_bf16_f32 v70, v186, v187
	v_cvt_pk_bf16_f32 v71, v194, v71
	ds_write_b128 v175, v[64:67]
	ds_write_b128 v175, v[68:71] offset:1024
	v_add_u32_e32 v224, s0, v202
	v_add_u32_e32 v224, v224, v213
	v_add_u32_e32 v224, 0x8000, v224
	v_xor_b32_e32 v225, s28, v224
	ds_read_b128 v[228:231], v225
	ds_read_b128 v[232:235], v225 offset:4096
	ds_read_b128 v[236:239], v225 offset:8192
	ds_read_b128 v[240:243], v225 offset:12288
	v_xor_b32_e32 v225, s27, v224
	ds_read_b128 v[244:247], v225
	ds_read_b128 v[248:251], v225 offset:4096
	ds_read_b128 v[72:75], v225 offset:8192
	ds_read_b128 v[76:79], v225 offset:12288
	v_add_u32_e32 v174, s56, v217
	s_add_i32 s59, s59, 64
	s_sub_i32 s58, s58, 64
	s_add_u32 s22, s22, 0x80
	s_addc_u32 s23, s23, 0
	s_add_u32 s20, s20, 0xc0000
	s_addc_u32 s21, s21, 0
	s_mov_b32 s63, s61
	s_mov_b32 s62, s60
	s_cmpk_eq_i32 s59, 0x11c0
	s_waitcnt lgkmcnt(4)
	v_mfma_f32_32x32x16_bf16 v[48:63], v[228:231], v[64:67], v[48:63]
	v_mfma_f32_32x32x16_bf16 v[32:47], v[232:235], v[64:67], v[32:47]
	v_mfma_f32_32x32x16_bf16 v[16:31], v[236:239], v[64:67], v[16:31]
	v_mfma_f32_32x32x16_bf16 v[0:15], v[240:243], v[64:67], v[0:15]
	s_waitcnt lgkmcnt(0)
	s_barrier
	ds_read_b128 v[176:179], v174
	ds_read_b128 v[180:183], v174 offset:1024
	v_xor_b32_e32 v225, s26, v224
	ds_read_b128 v[228:231], v225
	ds_read_b128 v[232:235], v225 offset:4096
	ds_read_b128 v[236:239], v225 offset:8192
	ds_read_b128 v[240:243], v225 offset:12288
	v_mfma_f32_32x32x16_bf16 v[48:63], v[244:247], v[68:71], v[48:63]
	v_mfma_f32_32x32x16_bf16 v[32:47], v[248:251], v[68:71], v[32:47]
	v_mfma_f32_32x32x16_bf16 v[16:31], v[72:75], v[68:71], v[16:31]
	v_mfma_f32_32x32x16_bf16 v[0:15], v[76:79], v[68:71], v[0:15]
	v_xor_b32_e32 v225, s5, v224
	ds_read_b128 v[244:247], v225
	ds_read_b128 v[248:251], v225 offset:4096
	ds_read_b128 v[72:75], v225 offset:8192
	ds_read_b128 v[76:79], v225 offset:12288
	s_waitcnt lgkmcnt(4)
	v_mfma_f32_32x32x16_bf16 v[48:63], v[228:231], v[176:179], v[48:63]
	v_mfma_f32_32x32x16_bf16 v[32:47], v[232:235], v[176:179], v[32:47]
	v_mfma_f32_32x32x16_bf16 v[16:31], v[236:239], v[176:179], v[16:31]
	v_mfma_f32_32x32x16_bf16 v[0:15], v[240:243], v[176:179], v[0:15]
	s_waitcnt vmcnt(0) lgkmcnt(0)
	s_barrier
	v_mfma_f32_32x32x16_bf16 v[48:63], v[244:247], v[180:183], v[48:63]
	v_mfma_f32_32x32x16_bf16 v[32:47], v[248:251], v[180:183], v[32:47]
	v_mfma_f32_32x32x16_bf16 v[16:31], v[72:75], v[180:183], v[16:31]
	v_mfma_f32_32x32x16_bf16 v[0:15], v[76:79], v[180:183], v[0:15]
	s_cbranch_scc1 .LBB0_817
